# bundle2: E-j + GU-tail MFMA slot split + resid-epilogue load hoist + FFT1 twiddle batch + redundant lgkmcnt waits removed + nt on P0 weight stores
# speedup vs baseline: 1.0043x; 1.0033x over previous
; #define PG8_STAGE(bufoff, gbase, voff) do { _Pragma("unroll") for (int _i = 0; _i < 2; ++_i) \
;         __builtin_amdgcn_global_load_lds((const unsigned*)((const char*)(gbase) + (voff)[_i]), (PG8_LAS unsigned*)(lds + (bufoff) + ldsw + _i * 8192), 16, 0, 0); } while (0)
; #define PG8_LDA(dst, b, h) do { _Pragma("unroll") for (int m = 0; m < 4; ++m) _Pragma("unroll") for (int k = 0; k < 2; ++k) dst[m][k] = *(const PG8_LAS bf16x8*)(lds + PG8_SA(b, h) + aoff + m * 2048 + k * 1024); } while (0)
; #define PG8_LDB(dst, b, h) do { _Pragma("unroll") for (int n = 0; n < 2; ++n) _Pragma("unroll") for (int k = 0; k < 2; ++k) dst[n][k] = *(const PG8_LAS bf16x8*)(lds + PG8_SB(b, h) + boff + n * 2048 + k * 1024); } while (0)
; #define PG8_MMA(ai, bj, At, Bt) do { __builtin_amdgcn_s_setprio(1); _Pragma("unroll") for (int m = 0; m < 4; ++m) _Pragma("unroll") for (int n = 0; n < 2; ++n) _Pragma("unroll") for (int k = 0; k < 2; ++k) \
;         acc[ai][bj][m][n] = __builtin_amdgcn_mfma_f32_16x16x32_bf16(Bt[n][k], At[m][k], acc[ai][bj][m][n], 0, 0, 0); __builtin_amdgcn_s_setprio(0); } while (0)
; #define PG8_WAIT_L(n) asm volatile("s_waitcnt lgkmcnt(" #n ")" ::: "memory")
; #define PG8_WAIT_VK do { if constexpr (HALFM) PG8_WAIT_V(6); else PG8_WAIT_V(8); } while (0)
; #define PG8_BAR __builtin_amdgcn_s_barrier()
; #define PG8_SCHED __builtin_amdgcn_sched_barrier(0)
; template <class Epi, class Sched, bool ALIGN_EPI = false, bool SP2 = false, bool HALFM = false, bool AMAP = false>
; __device__ __forceinline__ void gemm_phase(PG8_LAS unsigned char* lds, const Gemm g, const Sched& S, const Epi& E, int tid_in) {
;     ...
;             PG8_LDB(B0, 0, 0); PG8_LDB(B1, 0, 1); PG8_SCHED; PG8_LDA(At, 0, 0); if constexpr (!HALFM) PG8_STAGE(PG8_SA(1, 1), a1 + hstepA, voffA);
;             PG8_WAIT_VK; PG8_WAIT_L(0); PG8_BAR; PG8_MMA(0, 0, At, B0); PG8_MMA(0, 1, At, B1); PG8_BAR; PG8_SCHED;
;             if constexpr (!HALFM) { PG8_LDA(At, 0, 1); } PG8_STAGE(PG8_SB(0, 0), b2, voffB); PG8_STAGE(PG8_SB(0, 1), b2 + hstepB, voffB); PG8_STAGE(PG8_SA(0, 0), a2, voffA);
;             PG8_WAIT_VK; PG8_WAIT_L(0); PG8_BAR; if constexpr (!HALFM) { PG8_MMA(1, 0, At, B0); PG8_MMA(1, 1, At, B1); } PG8_BAR; PG8_SCHED;
.LBB0_191:
	s_add_i32 s36, 0, 0x10000
	s_cmp_eq_u32 s31, 28
	s_cselect_b64 vcc, -1, 0
	s_cselect_b32 s7, s25, s30
	s_cselect_b32 s6, s28, s29
	s_add_i32 s43, 0, 0x14000
	v_add_u32_e32 v80, s36, v126
	v_add_u32_e32 v96, s43, v126
	ds_read_b128 v[4:7], v80
	ds_read_b128 v[72:75], v80 offset:1024
	ds_read_b128 v[76:79], v80 offset:2048
	ds_read_b128 v[80:83], v80 offset:3072
	ds_read_b128 v[84:87], v96
	ds_read_b128 v[88:91], v96 offset:1024
	ds_read_b128 v[92:95], v96 offset:2048
	ds_read_b128 v[96:99], v96 offset:3072
	v_cndmask_b32_e32 v147, v1, v2, vcc
	v_cndmask_b32_e32 v146, v0, v3, vcc
	ds_read_b128 v[100:103], v129
	ds_read_b128 v[104:107], v129 offset:1024
	ds_read_b128 v[116:119], v129 offset:2048
	ds_read_b128 v[120:123], v129 offset:3072
	ds_read_b128 v[130:133], v129 offset:4096
	ds_read_b128 v[134:137], v129 offset:5120
	ds_read_b128 v[138:141], v129 offset:6144
	ds_read_b128 v[142:145], v129 offset:7168
	s_waitcnt vmcnt(6)
	s_waitcnt lgkmcnt(0)
	s_barrier
	s_setprio 1
	v_mfma_f32_16x16x32_bf16 v[68:71], v[4:7], v[100:103], v[68:71]
	v_mfma_f32_16x16x32_bf16 v[64:67], v[76:79], v[100:103], v[64:67]
	v_mfma_f32_16x16x32_bf16 v[52:55], v[4:7], v[116:119], v[52:55]
	v_mfma_f32_16x16x32_bf16 v[48:51], v[76:79], v[116:119], v[48:51]
	v_mfma_f32_16x16x32_bf16 v[36:39], v[4:7], v[130:133], v[36:39]
	v_mfma_f32_16x16x32_bf16 v[32:35], v[76:79], v[130:133], v[32:35]
	v_mfma_f32_16x16x32_bf16 v[16:19], v[76:79], v[138:141], v[16:19]
	v_mfma_f32_16x16x32_bf16 v[68:71], v[72:75], v[104:107], v[68:71]
	v_mfma_f32_16x16x32_bf16 v[64:67], v[80:83], v[104:107], v[64:67]
	v_mfma_f32_16x16x32_bf16 v[52:55], v[72:75], v[120:123], v[52:55]
	v_mfma_f32_16x16x32_bf16 v[48:51], v[80:83], v[120:123], v[48:51]
	v_mfma_f32_16x16x32_bf16 v[36:39], v[72:75], v[134:137], v[36:39]
	v_mfma_f32_16x16x32_bf16 v[32:35], v[80:83], v[134:137], v[32:35]
	v_mfma_f32_16x16x32_bf16 v[4:7], v[4:7], v[138:141], v[20:23]
	v_mfma_f32_16x16x32_bf16 v[16:19], v[80:83], v[142:145], v[16:19]
	v_mfma_f32_16x16x32_bf16 v[4:7], v[72:75], v[142:145], v[4:7]
	s_setprio 0
	s_barrier
	s_add_i32 s36, s36, s10
	v_lshl_add_u64 v[148:149], s[6:7], 0, v[176:177]
	s_mov_b32 m0, s36
	v_lshl_add_u64 v[150:151], s[6:7], 0, v[108:109]
	global_load_lds_dwordx4 v[148:149], off
	s_add_i32 m0, s36, 0x2000
	s_add_u32 s36, s6, 0x80000
	s_addc_u32 s37, s7, 0
	s_add_i32 s43, s43, s10
	global_load_lds_dwordx4 v[150:151], off
	v_lshl_add_u64 v[20:21], s[36:37], 0, v[176:177]
	s_mov_b32 m0, s43
	v_lshl_add_u64 v[152:153], v[146:147], 0, v[112:113]
	global_load_lds_dwordx4 v[20:21], off
	v_lshl_add_u64 v[20:21], s[36:37], 0, v[108:109]
	s_add_i32 m0, s43, 0x2000
	v_lshl_add_u64 v[146:147], v[146:147], 0, v[110:111]
	global_load_lds_dwordx4 v[20:21], off
	s_mov_b32 m0, s11
	s_nop 0
	global_load_lds_dwordx4 v[152:153], off
	s_mov_b32 m0, s15
	s_nop 0
	global_load_lds_dwordx4 v[146:147], off
	s_waitcnt vmcnt(6)
	s_waitcnt lgkmcnt(0)
	s_barrier
	s_setprio 1
	v_mfma_f32_16x16x32_bf16 v[20:23], v[84:87], v[100:103], v[60:63]
	v_mfma_f32_16x16x32_bf16 v[60:63], v[88:91], v[104:107], v[20:23]
	v_mfma_f32_16x16x32_bf16 v[20:23], v[92:95], v[100:103], v[56:59]
	v_mfma_f32_16x16x32_bf16 v[56:59], v[96:99], v[104:107], v[20:23]
	v_mfma_f32_16x16x32_bf16 v[20:23], v[84:87], v[116:119], v[44:47]
	v_mfma_f32_16x16x32_bf16 v[44:47], v[88:91], v[120:123], v[20:23]
	v_mfma_f32_16x16x32_bf16 v[20:23], v[92:95], v[116:119], v[40:43]
	v_mfma_f32_16x16x32_bf16 v[40:43], v[96:99], v[120:123], v[20:23]
	v_mfma_f32_16x16x32_bf16 v[20:23], v[84:87], v[130:133], v[28:31]
	v_mfma_f32_16x16x32_bf16 v[28:31], v[88:91], v[134:137], v[20:23]
	v_mfma_f32_16x16x32_bf16 v[20:23], v[92:95], v[130:133], v[24:27]
	v_mfma_f32_16x16x32_bf16 v[12:15], v[84:87], v[138:141], v[12:15]
	v_mfma_f32_16x16x32_bf16 v[8:11], v[92:95], v[138:141], v[8:11]
	v_mfma_f32_16x16x32_bf16 v[24:27], v[96:99], v[134:137], v[20:23]
	v_mfma_f32_16x16x32_bf16 v[12:15], v[88:91], v[142:145], v[12:15]
	v_mfma_f32_16x16x32_bf16 v[8:11], v[96:99], v[142:145], v[8:11]
	s_setprio 0
	s_barrier
; #define PG8_STAGE(bufoff, gbase, voff) do { _Pragma("unroll") for (int _i = 0; _i < 2; ++_i) \
;         __builtin_amdgcn_global_load_lds((const unsigned*)((const char*)(gbase) + (voff)[_i]), (PG8_LAS unsigned*)(lds + (bufoff) + ldsw + _i * 8192), 16, 0, 0); } while (0)
; #define PG8_LDA(dst, b, h) do { _Pragma("unroll") for (int m = 0; m < 4; ++m) _Pragma("unroll") for (int k = 0; k < 2; ++k) dst[m][k] = *(const PG8_LAS bf16x8*)(lds + PG8_SA(b, h) + aoff + m * 2048 + k * 1024); } while (0)
; #define PG8_LDB(dst, b, h) do { _Pragma("unroll") for (int n = 0; n < 2; ++n) _Pragma("unroll") for (int k = 0; k < 2; ++k) dst[n][k] = *(const PG8_LAS bf16x8*)(lds + PG8_SB(b, h) + boff + n * 2048 + k * 1024); } while (0)
; #define PG8_MMA(ai, bj, At, Bt) do { __builtin_amdgcn_s_setprio(1); _Pragma("unroll") for (int m = 0; m < 4; ++m) _Pragma("unroll") for (int n = 0; n < 2; ++n) _Pragma("unroll") for (int k = 0; k < 2; ++k) \
;         acc[ai][bj][m][n] = __builtin_amdgcn_mfma_f32_16x16x32_bf16(Bt[n][k], At[m][k], acc[ai][bj][m][n], 0, 0, 0); __builtin_amdgcn_s_setprio(0); } while (0)
; #define PG8_WAIT_L(n) asm volatile("s_waitcnt lgkmcnt(" #n ")" ::: "memory")
; #define PG8_WAIT_VK do { if constexpr (HALFM) PG8_WAIT_V(6); else PG8_WAIT_V(8); } while (0)
; #define PG8_BAR __builtin_amdgcn_s_barrier()
; #define PG8_SCHED __builtin_amdgcn_sched_barrier(0)
; template <class Epi, class Sched, bool ALIGN_EPI = false, bool SP2 = false, bool HALFM = false, bool AMAP = false>
; __device__ __forceinline__ void gemm_phase(PG8_LAS unsigned char* lds, const Gemm g, const Sched& S, const Epi& E, int tid_in) {
;     ...
;             PG8_LDB(B0, 1, 0); PG8_LDB(B1, 1, 1); PG8_SCHED; PG8_LDA(At, 1, 0); if constexpr (!HALFM) PG8_STAGE(PG8_SA(0, 1), a2 + hstepA, voffA);
;             PG8_WAIT_VK; PG8_WAIT_L(0); PG8_BAR; PG8_MMA(0, 0, At, B0); PG8_MMA(0, 1, At, B1); PG8_BAR; PG8_SCHED;
;             if constexpr (!HALFM) { PG8_LDA(At, 1, 1); } PG8_STAGE(PG8_SB(1, 0), b3, voffB); PG8_STAGE(PG8_SB(1, 1), b3 + hstepB, voffB); PG8_STAGE(PG8_SA(1, 0), a3, voffA);
;             PG8_WAIT_VK; PG8_WAIT_L(0); PG8_BAR; if constexpr (!HALFM) { PG8_MMA(1, 0, At, B0); PG8_MMA(1, 1, At, B1); } PG8_BAR; PG8_SCHED;
	s_add_i32 s36, 0, 0x18000
	s_add_i32 s37, 0, 0x1c000
	v_add_u32_e32 v80, s36, v126
	v_add_u32_e32 v96, s37, v126
	ds_read_b128 v[20:23], v80
	ds_read_b128 v[72:75], v80 offset:1024
	ds_read_b128 v[76:79], v80 offset:2048
	ds_read_b128 v[80:83], v80 offset:3072
	ds_read_b128 v[84:87], v96
	ds_read_b128 v[88:91], v96 offset:1024
	ds_read_b128 v[92:95], v96 offset:2048
	ds_read_b128 v[96:99], v96 offset:3072
	ds_read_b128 v[100:103], v129 offset:32768
	ds_read_b128 v[104:107], v129 offset:33792
	ds_read_b128 v[116:119], v129 offset:34816
	ds_read_b128 v[120:123], v129 offset:35840
	ds_read_b128 v[130:133], v129 offset:36864
	ds_read_b128 v[134:137], v129 offset:37888
	ds_read_b128 v[138:141], v129 offset:38912
	ds_read_b128 v[142:145], v129 offset:39936
	s_waitcnt vmcnt(6)
	s_waitcnt lgkmcnt(0)
	s_barrier
	s_setprio 1
	v_mfma_f32_16x16x32_bf16 v[4:7], v[20:23], v[138:141], v[4:7]
	v_mfma_f32_16x16x32_bf16 v[68:71], v[20:23], v[100:103], v[68:71]
	v_mfma_f32_16x16x32_bf16 v[64:67], v[76:79], v[100:103], v[64:67]
	v_mfma_f32_16x16x32_bf16 v[52:55], v[20:23], v[116:119], v[52:55]
	v_mfma_f32_16x16x32_bf16 v[48:51], v[76:79], v[116:119], v[48:51]
	v_mfma_f32_16x16x32_bf16 v[36:39], v[20:23], v[130:133], v[36:39]
	v_mfma_f32_16x16x32_bf16 v[32:35], v[76:79], v[130:133], v[32:35]
	v_mfma_f32_16x16x32_bf16 v[20:23], v[72:75], v[142:145], v[4:7]
	v_mfma_f32_16x16x32_bf16 v[4:7], v[76:79], v[138:141], v[16:19]
	v_mfma_f32_16x16x32_bf16 v[68:71], v[72:75], v[104:107], v[68:71]
	v_mfma_f32_16x16x32_bf16 v[64:67], v[80:83], v[104:107], v[64:67]
	v_mfma_f32_16x16x32_bf16 v[52:55], v[72:75], v[120:123], v[52:55]
	v_mfma_f32_16x16x32_bf16 v[48:51], v[80:83], v[120:123], v[48:51]
	v_mfma_f32_16x16x32_bf16 v[36:39], v[72:75], v[134:137], v[36:39]
	v_mfma_f32_16x16x32_bf16 v[32:35], v[80:83], v[134:137], v[32:35]
	v_mfma_f32_16x16x32_bf16 v[16:19], v[80:83], v[142:145], v[4:7]
	s_setprio 0
	s_barrier
	s_add_i32 s36, s36, s10
	s_nop 3
	v_lshl_add_u64 v[4:5], v[148:149], 0, s[66:67]
	s_mov_b32 m0, s36
	s_nop 0
	global_load_lds_dwordx4 v[4:5], off
	s_add_i32 m0, s36, 0x2000
	s_add_u32 s6, s6, 0x80080
	v_lshl_add_u64 v[4:5], v[150:151], 0, s[66:67]
	s_addc_u32 s7, s7, 0
	s_add_i32 s36, s37, s10
	global_load_lds_dwordx4 v[4:5], off
	v_lshl_add_u64 v[4:5], s[6:7], 0, v[176:177]
	s_mov_b32 m0, s36
	s_nop 0
	global_load_lds_dwordx4 v[4:5], off
	v_lshl_add_u64 v[4:5], s[6:7], 0, v[108:109]
	s_add_i32 m0, s36, 0x2000
	s_nop 0
	global_load_lds_dwordx4 v[4:5], off
	v_lshl_add_u64 v[4:5], v[152:153], 0, s[66:67]
	s_mov_b32 m0, s18
	s_nop 0
	global_load_lds_dwordx4 v[4:5], off
	v_lshl_add_u64 v[4:5], v[146:147], 0, s[66:67]
	s_mov_b32 m0, s19
	s_nop 0
	global_load_lds_dwordx4 v[4:5], off
	s_waitcnt vmcnt(6)
	s_waitcnt lgkmcnt(0)
	s_barrier
	s_setprio 1
	v_mfma_f32_16x16x32_bf16 v[4:7], v[84:87], v[100:103], v[60:63]
	v_mfma_f32_16x16x32_bf16 v[60:63], v[88:91], v[104:107], v[4:7]
	v_mfma_f32_16x16x32_bf16 v[4:7], v[92:95], v[100:103], v[56:59]
	v_mfma_f32_16x16x32_bf16 v[56:59], v[96:99], v[104:107], v[4:7]
	v_mfma_f32_16x16x32_bf16 v[4:7], v[84:87], v[116:119], v[44:47]
	v_mfma_f32_16x16x32_bf16 v[44:47], v[88:91], v[120:123], v[4:7]
	v_mfma_f32_16x16x32_bf16 v[4:7], v[92:95], v[116:119], v[40:43]
	v_mfma_f32_16x16x32_bf16 v[40:43], v[96:99], v[120:123], v[4:7]
	v_mfma_f32_16x16x32_bf16 v[4:7], v[84:87], v[130:133], v[28:31]
	v_mfma_f32_16x16x32_bf16 v[28:31], v[88:91], v[134:137], v[4:7]
	v_mfma_f32_16x16x32_bf16 v[4:7], v[92:95], v[130:133], v[24:27]
	v_mfma_f32_16x16x32_bf16 v[24:27], v[96:99], v[134:137], v[4:7]
	v_mfma_f32_16x16x32_bf16 v[4:7], v[84:87], v[138:141], v[12:15]
	v_mfma_f32_16x16x32_bf16 v[12:15], v[88:91], v[142:145], v[4:7]
	v_mfma_f32_16x16x32_bf16 v[4:7], v[92:95], v[138:141], v[8:11]
	v_mfma_f32_16x16x32_bf16 v[8:11], v[96:99], v[142:145], v[4:7]
	s_setprio 0
	s_barrier
	s_add_i32 s31, s31, 2
	s_add_u32 s29, s29, 0x100
	s_addc_u32 s30, s30, 0
	s_cmp_gt_u32 s31, 29
	v_lshl_add_u64 v[0:1], v[0:1], 0, s[68:69]
	s_cbranch_scc0 .LBB0_191
	s_and_b64 vcc, exec, s[22:23]
	s_cbranch_vccz .LBB0_194
	s_barrier
